# v44: gdn_prep conv head: the four serialised x loads issued together with the header loads (counted vmcnt waits)
# speedup vs baseline: 1.2039x; 1.0052x over previous
.LBB0_2860:
	s_mul_hi_i32 s0, s72, 0x7e07e07f
	s_lshr_b32 s1, s0, 31
	s_ashr_i32 s0, s0, 5
	s_add_i32 s0, s0, s1
	s_mul_i32 s1, s0, 0x41
	s_sub_i32 s1, s72, s1
	s_and_b32 s40, s0, 7
	s_lshr_b32 s41, s0, 3
	s_lshl_b32 s0, s1, 6
	s_sub_i32 s46, s0, 48
	v_add_u32_e32 v41, s46, v39
	s_mulk_i32 s41, 0x1010
	v_max_i32_e32 v0, 2, v41
	v_lshl_or_b32 v4, s40, 6, v16
	v_add3_u32 v0, s41, -2, v0
	v_lshlrev_b32_e32 v20, 2, v4
	v_ashrrev_i32_e32 v1, 31, v0
	v_lshl_add_u64 v[48:49], s[82:83], 0, v[20:21]
	s_movk_i32 s0, 0x1000
	v_lshlrev_b64 v[0:1], 12, v[0:1]
	v_add_co_u32_e32 v50, vcc, s0, v48
	s_barrier
	v_lshl_add_u64 v[0:1], s[42:43], 0, v[0:1]
	s_waitcnt lgkmcnt(0)
	v_max_i32_e32 v2, 1, v41
	v_addc_co_u32_e32 v51, vcc, 0, v49, vcc
	global_load_dword v63, v20, s[82:83]
	global_load_dword v62, v[50:51], off offset:2048
	v_lshlrev_b32_e32 v20, 1, v4
	v_cmp_lt_i32_e64 s[34:35], -1, v41
	v_add3_u32 v2, s41, -1, v2
	v_add_u32_e32 v6, 0x1a0, v4
	v_lshl_add_u64 v[4:5], v[0:1], 0, v[20:21]
	v_cndmask_b32_e64 v0, 0, v41, s[34:35]
	v_ashrrev_i32_e32 v3, 31, v2
	v_add_u32_e32 v0, s41, v0
	v_lshlrev_b64 v[2:3], 12, v[2:3]
	v_ashrrev_i32_e32 v1, 31, v0
	v_lshl_add_u64 v[2:3], s[42:43], 0, v[2:3]
	v_lshlrev_b64 v[0:1], 12, v[0:1]
	v_add_co_u32_e32 v58, vcc, s33, v48
	v_lshl_add_u64 v[14:15], v[2:3], 0, v[20:21]
	v_lshl_add_u64 v[44:45], s[42:43], 0, v[0:1]
	v_lshlrev_b32_e32 v66, 1, v6
	v_mov_b32_e32 v67, v21
	v_addc_co_u32_e32 v59, vcc, 0, v49, vcc
	global_load_ushort v2, v[14:15], off offset:832
	global_load_ushort v3, v[4:5], off offset:832
	v_lshl_add_u64 v[0:1], v[44:45], 0, v[66:67]
	s_movk_i32 s0, 0x4000
	global_load_ushort v6, v[0:1], off
	v_add_co_u32_e32 v46, vcc, s0, v48
	v_max_i32_e32 v0, 3, v41
	s_nop 0
	v_addc_co_u32_e32 v47, vcc, 0, v49, vcc
	global_load_dword v65, v[58:59], off
	global_load_dword v64, v[46:47], off offset:2048
	v_add3_u32 v0, s41, -3, v0
	v_ashrrev_i32_e32 v1, 31, v0
	v_lshlrev_b64 v[0:1], 12, v[0:1]
	v_lshl_add_u64 v[56:57], s[42:43], 0, v[0:1]
	v_lshl_add_u64 v[234:235], v[56:57], 0, v[20:21]
	global_load_ushort v230, v[234:235], off offset:832
	v_or_b32_e32 v236, 1, v41
	v_cndmask_b32_e64 v236, 0, v236, s[34:35]
	v_add_u32_e32 v236, s41, v236
	v_ashrrev_i32_e32 v237, 31, v236
	v_lshlrev_b64 v[236:237], 12, v[236:237]
	v_lshl_add_u64 v[236:237], s[42:43], 0, v[236:237]
	v_lshl_add_u64 v[236:237], v[236:237], 0, v[66:67]
	global_load_ushort v231, v[236:237], off
	v_or_b32_e32 v236, 2, v41
	v_cndmask_b32_e64 v236, 0, v236, s[34:35]
	v_add_u32_e32 v236, s41, v236
	v_ashrrev_i32_e32 v237, 31, v236
	v_lshlrev_b64 v[236:237], 12, v[236:237]
	v_lshl_add_u64 v[236:237], s[42:43], 0, v[236:237]
	v_lshl_add_u64 v[236:237], v[236:237], 0, v[66:67]
	global_load_ushort v232, v[236:237], off
	v_or_b32_e32 v236, 3, v41
	v_cndmask_b32_e64 v236, 0, v236, s[34:35]
	v_add_u32_e32 v236, s41, v236
	v_ashrrev_i32_e32 v237, 31, v236
	v_lshlrev_b64 v[236:237], 12, v[236:237]
	v_lshl_add_u64 v[236:237], s[42:43], 0, v[236:237]
	v_lshl_add_u64 v[236:237], v[236:237], 0, v[66:67]
	global_load_ushort v233, v[236:237], off
	v_cmp_lt_i32_e64 s[28:29], 0, v41
	v_cmp_lt_i32_e64 s[30:31], 1, v41
	v_cmp_lt_i32_e32 vcc, 2, v41
	v_cmp_gt_i32_e64 s[36:37], 0, v41
	s_waitcnt vmcnt(8)
	v_lshlrev_b32_e32 v1, 16, v2
	s_waitcnt vmcnt(7)
	v_lshlrev_b32_e32 v0, 16, v3
	v_cndmask_b32_e64 v3, 0, v1, s[28:29]
	v_cndmask_b32_e64 v2, 0, v0, s[30:31]
	s_waitcnt vmcnt(6)
	v_lshlrev_b32_e32 v8, 16, v6
	v_mov_b32_e32 v0, v21
	s_and_saveexec_b64 s[0:1], s[34:35]
	s_cbranch_execz .LBB0_2862
	v_lshl_add_u64 v[0:1], v[56:57], 0, v[20:21]
	v_mov_b32_e32 v0, v2
	v_mov_b32_e32 v9, v3
	s_waitcnt vmcnt(4)
	v_pk_mul_f32 v[6:7], v[64:65], v[8:9]
	s_waitcnt vmcnt(3)
	v_lshlrev_b32_e32 v1, 16, v230
	v_cndmask_b32_e32 v1, 0, v1, vcc
	v_pk_mul_f32 v[0:1], v[62:63], v[0:1]
	s_nop 0
	v_add_f32_e32 v0, v0, v1
	v_add_f32_e32 v0, v7, v0
	v_add_f32_e32 v0, v6, v0
	v_mul_f32_e32 v1, 0xbfb8aa3b, v0
	v_exp_f32_e32 v1, v1
	s_nop 0
	v_add_f32_e32 v1, 1.0, v1
	v_rcp_f32_e32 v1, v1
	s_nop 0
	v_mul_f32_e32 v0, v0, v1
.LBB0_2862:
	s_or_b64 exec, exec, s[0:1]
	ds_write_b32 v90, v0
	v_or_b32_e32 v0, 1, v41
	v_cndmask_b32_e64 v0, 0, v0, s[34:35]
	v_add_u32_e32 v0, s41, v0
	v_ashrrev_i32_e32 v1, 31, v0
	v_lshlrev_b64 v[0:1], 12, v[0:1]
	v_lshl_add_u64 v[52:53], s[42:43], 0, v[0:1]
	v_lshl_add_u64 v[0:1], v[52:53], 0, v[66:67]
	v_mov_b32_e32 v6, 0
	s_waitcnt vmcnt(2)
	v_lshlrev_b32_e32 v9, 16, v231
	v_mov_b32_e32 v0, 0
	s_and_saveexec_b64 s[0:1], s[34:35]
	s_cbranch_execz .LBB0_2864
	v_mov_b32_e32 v0, v63
	v_mov_b32_e32 v1, v62
	v_pk_mul_f32 v[0:1], v[0:1], v[2:3]
	v_mov_b32_e32 v10, v65
	v_mov_b32_e32 v11, v64
	v_pk_mul_f32 v[10:11], v[10:11], v[8:9]
	v_add_f32_e32 v0, v0, v1
	v_add_f32_e32 v0, v10, v0
	v_add_f32_e32 v0, v0, v11
	v_mul_f32_e32 v1, 0xbfb8aa3b, v0
	v_exp_f32_e32 v1, v1
	s_nop 0
	v_add_f32_e32 v1, 1.0, v1
	v_rcp_f32_e32 v1, v1
	s_nop 0
	v_mul_f32_e32 v0, v0, v1
.LBB0_2864:
	s_or_b64 exec, exec, s[0:1]
	ds_write_b32 v90, v0 offset:260
	v_or_b32_e32 v0, 2, v41
	v_cndmask_b32_e64 v0, 0, v0, s[34:35]
	v_add_u32_e32 v0, s41, v0
	v_ashrrev_i32_e32 v1, 31, v0
	v_lshlrev_b64 v[0:1], 12, v[0:1]
	v_lshl_add_u64 v[0:1], s[42:43], 0, v[0:1]
	v_mov_b32_e32 v67, v21
	v_lshl_add_u64 v[10:11], v[0:1], 0, v[66:67]
	s_waitcnt vmcnt(1)
	v_lshlrev_b32_e32 v69, 16, v232
	s_and_saveexec_b64 s[0:1], s[34:35]
	s_cbranch_execz .LBB0_2866
	v_mov_b32_e32 v2, v8
	v_pk_mul_f32 v[2:3], v[62:63], v[2:3]
	v_mov_b32_e32 v6, v65
	v_mov_b32_e32 v7, v64
	v_mov_b32_e32 v68, v9
	v_pk_mul_f32 v[6:7], v[6:7], v[68:69]
	v_add_f32_e32 v2, v2, v3
	v_add_f32_e32 v2, v2, v6
	v_add_f32_e32 v2, v2, v7
	v_mul_f32_e32 v3, 0xbfb8aa3b, v2
	v_exp_f32_e32 v3, v3
	s_nop 0
	v_add_f32_e32 v3, 1.0, v3
	v_rcp_f32_e32 v3, v3
	s_nop 0
	v_mul_f32_e32 v6, v2, v3
.LBB0_2866:
	s_or_b64 exec, exec, s[0:1]
	v_or_b32_e32 v2, 3, v41
	v_cndmask_b32_e64 v2, 0, v2, s[34:35]
	v_add_u32_e32 v2, s41, v2
	v_ashrrev_i32_e32 v3, 31, v2
	v_lshlrev_b64 v[2:3], 12, v[2:3]
	v_lshl_add_u64 v[2:3], s[42:43], 0, v[2:3]
	ds_write_b32 v90, v6 offset:520
	v_lshl_add_u64 v[6:7], v[2:3], 0, v[66:67]
	s_waitcnt vmcnt(0)
	v_lshlrev_b32_e32 v13, 16, v233
	v_mov_b32_e32 v6, 0
	s_and_saveexec_b64 s[0:1], s[34:35]
	s_cbranch_execz .LBB0_2868
	v_mov_b32_e32 v6, v63
	v_mov_b32_e32 v7, v62
	v_pk_mul_f32 v[6:7], v[6:7], v[8:9]
	v_mov_b32_e32 v10, v65
	v_mov_b32_e32 v11, v64
	v_mov_b32_e32 v12, v69
	v_pk_mul_f32 v[10:11], v[10:11], v[12:13]
	v_add_f32_e32 v6, v6, v7
	v_add_f32_e32 v6, v6, v10
	v_add_f32_e32 v6, v6, v11
	v_mul_f32_e32 v7, 0xbfb8aa3b, v6
	v_exp_f32_e32 v7, v7
	s_nop 0
	v_add_f32_e32 v7, 1.0, v7
	v_rcp_f32_e32 v7, v7
	s_nop 0
	v_mul_f32_e32 v6, v6, v7
